# v22 + grid barrier between GLU GEMM and out GEMM replaced by per-panel counters (4 producer blocks per 256-row panel, release fence + atomic, poll + L1 invalidate)
# baseline (speedup 1.0000x reference)
; __device__ __forceinline__ unsigned xb_ld(unsigned* p)              { return __hip_atomic_load(p, __ATOMIC_RELAXED, __HIP_MEMORY_SCOPE_AGENT); }
; __device__ __forceinline__ unsigned xb_add(unsigned* p, unsigned v) { return __hip_atomic_fetch_add(p, v, __ATOMIC_RELAXED, __HIP_MEMORY_SCOPE_AGENT); }
; #define XB_SPIN(cond, bar) do { unsigned _sp = 0; while (cond) { __builtin_amdgcn_s_sleep(1); \
;     if ((++_sp & 255u) == 0u) { if (xb_ld(&(bar)[XB_TMO])) break; if (_sp > XB_SPIN_CAP) { atomicAdd(&(bar)[XB_TMO], 1u); break; } } } } while (0)
; __device__ __forceinline__ void xcd_barrier(const XcdBarrier& b) {
;     asm volatile("s_waitcnt vmcnt(0)" ::: "memory");
;     __syncthreads();
;     if (threadIdx.x == 0) {
;         unsigned* bar = b.bar;
;         __builtin_amdgcn_s_waitcnt(0);
;         unsigned nloc = b.st[0], nx = b.st[1];
;         if (nloc == 0u) { xcd_barrier_complete(bar, b.x, nloc, nx); b.st[0] = nloc; b.st[1] = nx; }
;         const unsigned old = xb_add(&bar[XB_XSUB(b.x)], 1u);
;         const unsigned gen = old / nloc;
;         if (old + 1u == (gen + 1u) * nloc) {
;             __builtin_amdgcn_fence(__ATOMIC_RELEASE, "agent");
;             asm volatile("s_waitcnt vmcnt(0)" ::: "memory");
;             const unsigned og = xb_add(&bar[XB_TOP], 1u);
;             const unsigned tg = og / nx;
;             if (og + 1u == (tg + 1u) * nx) xb_add(&bar[XB_TOPGEN], 1u);
;             else XB_SPIN(xb_ld(&bar[XB_TOPGEN]) == tg, bar);
;             __builtin_amdgcn_fence(__ATOMIC_ACQUIRE, "agent");
;             xb_add(&bar[XB_XGEN(b.x)], 1u);
;             asm volatile("s_waitcnt vmcnt(0)" ::: "memory");
;         } else {
;             XB_SPIN(xb_ld(&bar[XB_XGEN(b.x)]) == gen, bar);
;             __builtin_amdgcn_fence(__ATOMIC_ACQUIRE, "agent");
;             asm volatile("s_waitcnt vmcnt(0)" ::: "memory");
;         }
;     }
;     __syncthreads();
; }
; __global__ void __launch_bounds__(512, 2) fwd_megakernel(Args a) {
;     ...
;     SEAM(10);
;     if (IN(11)) { pg8::Gemm g{H, (const bf16_t*)(ws + WS_WSOUT), NLAT, D, D}; PanelOrder S; S.init(NLAT, G, bid);
;         EpiResidNorm<true> E{nullptr, (bf16_t*)(ws + WS_X1), a.out, mod1, a.in[21], nullptr, nullptr, (float*)(ws + WS_STAT) + 68 * 1024, (unsigned*)(ws + WS_CNT) + 68 * 64};
;         pg8::gemm_phase<EpiResidNorm<true>, PanelOrder>(lds, g, S, E); }
.LBB0_841:
	s_cmp_gt_i32 s69, 11
	s_cselect_b64 s[2:3], -1, 0
	s_and_b64 s[0:1], s[0:1], s[2:3]
	s_andn2_b64 vcc, exec, s[0:1]
	s_cbranch_vccnz .LBB0_895
	s_waitcnt vmcnt(0)
	s_waitcnt vmcnt(0)
	s_barrier
	s_and_saveexec_b64 s[0:1], s[10:11]
	s_cbranch_execz .LBB0_894
	buffer_wbl2 sc1
	s_waitcnt vmcnt(0)
	s_and_b32 s96, s12, 7
	s_lshl_b32 s96, s96, 3
	s_bfe_u32 s97, s12, 0x30003
	s_add_u32 s96, s96, s97
	s_lshl_b32 s96, s96, 2
	s_add_u32 s98, s30, 0x23700
	s_addc_u32 s99, s31, 0
	v_mov_b32_e32 v252, s96
	v_mov_b32_e32 v253, 1
	global_atomic_add v252, v253, s[98:99]
	s_and_b32 s96, s12, 7
	s_lshl_b32 s96, s96, 3
	s_lshr_b32 s97, s12, 5
	s_add_u32 s96, s96, s97
	s_lshl_b32 s96, s96, 2
	v_mov_b32_e32 v252, s96
	s_mov_b32 s100, 0
.Lseam10_spin:
	global_load_dword v253, v252, s[98:99] sc1
	s_waitcnt vmcnt(0)
	v_readfirstlane_b32 s101, v253
	s_nop 3
	s_cmpk_ge_u32 s101, 4
	s_cbranch_scc1 .Lseam10_ok
	s_sleep 1
	s_add_u32 s100, s100, 1
	s_cmp_lt_u32 s100, 0x2000
	s_cbranch_scc1 .Lseam10_spin
.Lseam10_ok:
	buffer_inv sc1
	s_waitcnt vmcnt(0)
.LBB0_894:
	s_or_b64 exec, exec, s[0:1]
	s_waitcnt lgkmcnt(0)
	s_barrier
